# gla_c: counted vmcnt waits - the q/k stage waits only for the q/k rows, the V stage only for the V rows and the S_f staging rows
# baseline (speedup 1.0000x reference)
.LBB0_828:
	s_or_b64 exec, exec, s[0:1]
	s_waitcnt lgkmcnt(1)
	v_lshl_add_u32 v56, v126, 2, 0
	v_add_u32_e32 v56, 0x10600, v56
	ds_write_b32 v56, v125
	s_waitcnt lgkmcnt(0)
	s_barrier
	ds_read_b32 v56, v88 offset:1024
	s_waitcnt lgkmcnt(0)
	v_cndmask_b32_e64 v57, 0, v56, s[8:9]
	v_cndmask_b32_e64 v58, 0, v56, s[10:11]
	v_cndmask_b32_e64 v57, v58, v57, s[4:5]
	v_add_f32_e32 v2, v2, v57
	v_add_f32_e32 v3, v3, v57
	v_add_f32_e32 v4, v4, v57
	v_add_f32_e32 v5, v5, v57
	v_add_f32_e32 v6, v6, v57
	v_add_f32_e32 v7, v7, v57
	v_add_f32_e32 v8, v8, v57
	v_add_f32_e32 v9, v9, v57
	v_add_f32_e32 v10, v10, v57
	v_add_f32_e32 v11, v11, v57
	v_add_f32_e32 v12, v12, v57
	v_add_f32_e32 v13, v13, v57
	ds_write2_b32 v49, v2, v3 offset0:2 offset1:131
	ds_write2_b32 v51, v4, v5 offset0:4 offset1:133
	ds_write2_b32 v53, v6, v7 offset0:6 offset1:135
	ds_write2_b32 v114, v8, v9 offset0:8 offset1:137
	ds_write2_b32 v117, v10, v11 offset0:10 offset1:139
	ds_write2_b32 v120, v12, v13 offset0:12 offset1:141
	v_add_f32_e32 v2, v0, v57
	v_add_f32_e32 v1, v1, v57
	v_add_f32_e32 v14, v14, v57
	v_add_f32_e32 v15, v15, v57
	v_add_f32_e32 v16, v16, v57
	v_add_f32_e32 v17, v17, v57
	v_add_f32_e32 v18, v18, v57
	v_add_f32_e32 v19, v19, v57
	v_add_f32_e32 v20, v20, v57
	v_add_f32_e32 v21, v21, v57
	v_add_f32_e32 v22, v22, v57
	ds_write2_b32 v112, v2, v1 offset1:129
	ds_write2_b32 v115, v14, v15 offset0:14 offset1:143
	ds_write2_b32 v118, v16, v17 offset0:16 offset1:145
	ds_write2_b32 v121, v18, v19 offset0:18 offset1:147
	ds_write2_b32 v123, v20, v21 offset0:20 offset1:149
	v_add_f32_e32 v1, v23, v57
	ds_write2_b32 v124, v22, v1 offset0:22 offset1:151
	v_add_f32_e32 v1, v24, v57
	v_add_f32_e32 v2, v25, v57
	ds_write2_b32 v122, v1, v2 offset0:24 offset1:153
	v_add_f32_e32 v1, v26, v57
	v_add_f32_e32 v2, v27, v57
	ds_write2_b32 v119, v1, v2 offset0:26 offset1:155
	v_add_f32_e32 v1, v28, v57
	v_add_f32_e32 v2, v29, v57
	ds_write2_b32 v116, v1, v2 offset0:28 offset1:157
	v_add_f32_e32 v1, v54, v57
	v_add_f32_e32 v2, v55, v57
	ds_write2_b32 v113, v1, v2 offset0:30 offset1:159
	s_and_saveexec_b64 s[0:1], s[10:11]
	v_cndmask_b32_e64 v0, v0, v56, s[4:5]
	v_cndmask_b32_e64 v1, v56, v55, s[4:5]
	v_add_f32_e32 v0, v0, v1
	ds_write_b32 v89, v0
	s_or_b64 exec, exec, s[0:1]
	v_or_b32_e32 v2, s44, v144
	v_mov_b64_e32 v[0:1], s[68:69]
	v_mad_i64_i32 v[0:1], s[0:1], v2, s79, v[0:1]
	s_lshl_b32 s70, s70, 1
	v_lshl_add_u64 v[0:1], v[0:1], 0, s[70:71]
	v_mov_b32_e32 v49, v31
	v_lshl_add_u64 v[16:17], v[0:1], 0, v[48:49]
	s_waitcnt vmcnt(10) lgkmcnt(0)
	s_barrier
	v_mov_b32_e32 v12, v150
	v_mov_b32_e32 v13, v151
	v_mov_b32_e32 v14, v152
	v_mov_b32_e32 v15, v153
	v_mov_b32_e32 v8, v154
	v_mov_b32_e32 v9, v155
	v_mov_b32_e32 v10, v156
	v_mov_b32_e32 v11, v157
	v_add_u32_e32 v0, 0x8100, v90
	v_add_u32_e32 v1, 0x8108, v90
	v_add_u32_e32 v2, 0x8110, v90
	ds_read2_b32 v[18:19], v90 offset1:1
	ds_read2_b32 v[20:21], v90 offset0:2 offset1:3
	ds_read2_b32 v[22:23], v90 offset0:4 offset1:5
	ds_read2_b32 v[24:25], v0 offset1:1
	ds_read2_b32 v[26:27], v1 offset1:1
	ds_read2_b32 v[28:29], v2 offset1:1
	v_mov_b32_e32 v4, v158
	v_mov_b32_e32 v5, v159
	v_mov_b32_e32 v6, v160
	v_mov_b32_e32 v7, v161
	v_mov_b32_e32 v0, v162
	v_mov_b32_e32 v1, v163
	v_mov_b32_e32 v2, v164
	v_mov_b32_e32 v3, v165
	s_lshl_b32 s98, s85, 3
	s_lshl_b32 s99, s86, 1
	s_or_b32 s98, s99, s98
	s_or_b32 s98, s98, 1
	s_ashr_i32 s99, s98, 31
	s_lshl_b64 s[98:99], s[98:99], 21
	s_add_u32 s98, s98, s52
	s_addc_u32 s99, s99, s53
	s_lshl_b32 s100, s45, 15
	s_add_u32 s98, s98, s100
	s_addc_u32 s99, s99, 0
	v_readlane_b32 s100, v244, 25
	v_lshrrev_b32_e32 v210, 4, v144
	v_and_b32_e32 v211, 15, v144
	v_lshl_add_u32 v210, s100, 4, v210
	v_lshlrev_b32_e32 v210, 8, v210
	v_lshl_add_u32 v210, v211, 4, v210
	global_load_dwordx4 v[150:153], v210, s[98:99]
	global_load_dwordx4 v[154:157], v210, s[98:99] offset:1024
	global_load_dwordx4 v[158:161], v210, s[98:99] offset:2048
	global_load_dwordx4 v[162:165], v210, s[98:99] offset:3072
	s_waitcnt lgkmcnt(5)
	v_mul_f32_e32 v49, 0x3fb8aa3b, v18
	v_mul_f32_e32 v51, 0xbfb8aa3b, v18
	v_mul_f32_e32 v53, 0x3fb8aa3b, v19
	v_mul_f32_e32 v54, 0xbfb8aa3b, v19
	s_waitcnt lgkmcnt(4)
	v_mul_f32_e32 v55, 0x3fb8aa3b, v20
	v_mul_f32_e32 v56, 0xbfb8aa3b, v20
	v_mul_f32_e32 v57, 0x3fb8aa3b, v21
	v_mul_f32_e32 v58, 0xbfb8aa3b, v21
	s_waitcnt lgkmcnt(3)
	v_mul_f32_e32 v59, 0x3fb8aa3b, v22
	v_mul_f32_e32 v60, 0xbfb8aa3b, v22
	v_mul_f32_e32 v61, 0x3fb8aa3b, v23
	v_mul_f32_e32 v62, 0xbfb8aa3b, v23
	s_waitcnt lgkmcnt(2)
	v_mul_f32_e32 v63, 0xbfb8aa3b, v25
	s_waitcnt lgkmcnt(1)
	v_mul_f32_e32 v64, 0x3fb8aa3b, v26
	v_mul_f32_e32 v65, 0xbfb8aa3b, v26
	v_mul_f32_e32 v66, 0x3fb8aa3b, v27
	v_mul_f32_e32 v67, 0xbfb8aa3b, v27
	v_exp_f32_e32 v18, v49
	v_exp_f32_e32 v20, v51
	v_mul_f32_e32 v49, 0x3fb8aa3b, v24
	v_mul_f32_e32 v51, 0xbfb8aa3b, v24
	v_exp_f32_e32 v19, v53
	v_exp_f32_e32 v21, v54
	v_mul_f32_e32 v53, 0x3fb8aa3b, v25
	v_exp_f32_e32 v22, v55
	v_exp_f32_e32 v24, v56
	v_exp_f32_e32 v23, v57
	v_exp_f32_e32 v25, v58
	v_exp_f32_e32 v26, v59
	v_exp_f32_e32 v54, v60
	v_exp_f32_e32 v27, v61
	v_exp_f32_e32 v55, v62
	v_exp_f32_e32 v59, v63
	v_exp_f32_e32 v60, v64
	v_exp_f32_e32 v62, v65
	v_exp_f32_e32 v61, v66
	v_exp_f32_e32 v63, v67
	s_waitcnt lgkmcnt(0)
	v_mul_f32_e32 v68, 0x3fb8aa3b, v28
	v_mul_f32_e32 v70, 0x3fb8aa3b, v29
	v_exp_f32_e32 v64, v68
	v_exp_f32_e32 v65, v70
	v_exp_f32_e32 v56, v49
	v_exp_f32_e32 v57, v53
	v_mul_f32_e32 v28, 0xbfb8aa3b, v28
	v_exp_f32_e32 v28, v28
	v_exp_f32_e32 v58, v51
	s_lshl_b32 s1, s86, 1
	s_lshl_b32 s45, s45, 15
	v_lshlrev_b32_e32 v66, 16, v12
	v_and_b32_e32 v67, 0xffff0000, v12
	v_lshlrev_b32_e32 v12, 16, v13
	v_and_b32_e32 v13, 0xffff0000, v13
	v_lshlrev_b32_e32 v68, 16, v8
	v_and_b32_e32 v69, 0xffff0000, v8
	v_lshlrev_b32_e32 v8, 16, v9
	v_and_b32_e32 v9, 0xffff0000, v9
	v_pk_mul_f32 v[66:67], v[66:67], s[74:75] op_sel_hi:[1,0]
	v_pk_mul_f32 v[12:13], v[12:13], s[74:75] op_sel_hi:[1,0]
	v_pk_mul_f32 v[62:63], v[62:63], v[8:9]
	v_pk_mul_f32 v[24:25], v[24:25], v[8:9]
	v_pk_mul_f32 v[8:9], v[66:67], v[18:19]
	v_pk_mul_f32 v[18:19], v[12:13], v[60:61]
	v_pk_mul_f32 v[12:13], v[12:13], v[22:23]
	v_lshlrev_b32_e32 v22, 16, v14
	v_and_b32_e32 v23, 0xffff0000, v14
	v_mul_f32_e32 v14, 0xbfb8aa3b, v29
	v_pk_mul_f32 v[22:23], v[22:23], s[74:75] op_sel_hi:[1,0]
	v_exp_f32_e32 v29, v14
	v_add_u32_e32 v14, 24, v90
	v_pk_mul_f32 v[60:61], v[22:23], v[64:65]
	v_pk_mul_f32 v[22:23], v[22:23], v[26:27]
	ds_read2st64_b32 v[26:27], v14 offset1:129
	v_pk_mul_f32 v[56:57], v[66:67], v[56:57]
	ds_read2st64_b32 v[66:67], v91 offset1:129
	v_lshlrev_b32_e32 v64, 16, v10
	v_and_b32_e32 v65, 0xffff0000, v10
	s_waitcnt lgkmcnt(1)
	v_mul_f32_e32 v10, 0x3fb8aa3b, v26
	v_pk_mul_f32 v[28:29], v[28:29], v[64:65]
	v_pk_mul_f32 v[54:55], v[54:55], v[64:65]
	v_exp_f32_e32 v64, v10
	v_mul_f32_e32 v10, 0xbfb8aa3b, v26
	v_exp_f32_e32 v26, v10
	v_mul_f32_e32 v10, 0x3fb8aa3b, v27
	v_pk_mul_f32 v[58:59], v[58:59], v[68:69]
	v_pk_mul_f32 v[20:21], v[20:21], v[68:69]
	v_exp_f32_e32 v68, v10
	v_mul_f32_e32 v10, 0xbfb8aa3b, v27
	v_exp_f32_e32 v14, v10
	s_waitcnt lgkmcnt(0)
	v_mul_f32_e32 v10, 0x3fb8aa3b, v66
	v_exp_f32_e32 v65, v10
	v_mul_f32_e32 v10, 0xbfb8aa3b, v66
	v_exp_f32_e32 v27, v10
	v_mul_f32_e32 v10, 0x3fb8aa3b, v67
	v_exp_f32_e32 v69, v10
	v_mul_f32_e32 v10, 0xbfb8aa3b, v67
	v_lshlrev_b32_e32 v70, 16, v15
	v_and_b32_e32 v71, 0xffff0000, v15
	v_exp_f32_e32 v15, v10
	v_pk_mul_f32 v[70:71], v[70:71], s[74:75] op_sel_hi:[1,0]
	v_lshlrev_b32_e32 v10, 16, v11
	v_pk_mul_f32 v[64:65], v[70:71], v[64:65]
	v_and_b32_e32 v11, 0xffff0000, v11
	v_pk_mul_f32 v[14:15], v[14:15], v[10:11]
	v_pk_mul_f32 v[26:27], v[26:27], v[10:11]
	v_cvt_pk_bf16_f32 v8, v8, v9
	v_cvt_pk_bf16_f32 v9, v12, v13
	v_cvt_pk_bf16_f32 v10, v22, v23
	v_cvt_pk_bf16_f32 v11, v64, v65
	v_pk_mul_f32 v[68:69], v[70:71], v[68:69]
	ds_write_b128 v92, v[8:11]
	v_cvt_pk_bf16_f32 v8, v20, v21
	v_cvt_pk_bf16_f32 v9, v24, v25
	v_cvt_pk_bf16_f32 v10, v54, v55
	v_cvt_pk_bf16_f32 v11, v26, v27
	ds_write_b128 v92, v[8:11] offset:17408
	v_cvt_pk_bf16_f32 v8, v56, v57
	v_cvt_pk_bf16_f32 v9, v18, v19
	v_cvt_pk_bf16_f32 v10, v60, v61
	v_cvt_pk_bf16_f32 v11, v68, v69
	ds_write_b128 v92, v[8:11] offset:34816
	v_cvt_pk_bf16_f32 v8, v58, v59
	v_cvt_pk_bf16_f32 v9, v62, v63
	v_cvt_pk_bf16_f32 v10, v28, v29
	v_cvt_pk_bf16_f32 v11, v14, v15
	ds_write_b128 v92, v[8:11] offset:52224
	ds_read2_b32 v[8:9], v90 offset0:64 offset1:65
	v_add_u32_e32 v10, 0x8200, v90
	ds_read2_b32 v[10:11], v10 offset1:1
	ds_read2_b32 v[12:13], v90 offset0:66 offset1:67
	ds_read2_b32 v[14:15], v90 offset0:68 offset1:69
	ds_read2_b32 v[18:19], v90 offset0:70 offset1:71
	v_add_u32_e32 v21, 0x8208, v90
	v_add_u32_e32 v24, 0x8210, v90
	v_add_u32_e32 v26, 0x8218, v90
	ds_read2_b32 v[22:23], v21 offset1:1
	ds_read2_b32 v[24:25], v24 offset1:1
	ds_read2_b32 v[26:27], v26 offset1:1
	s_waitcnt lgkmcnt(6)
	v_mul_f32_e32 v21, 0x3fb8aa3b, v10
	v_mul_f32_e32 v20, 0x3fb8aa3b, v8
	v_exp_f32_e32 v28, v21
	v_mul_f32_e32 v21, 0x3fb8aa3b, v9
	v_mul_f32_e32 v29, 0x3fb8aa3b, v11
	v_exp_f32_e32 v20, v20
	v_mul_f32_e32 v8, 0xbfb8aa3b, v8
	v_mul_f32_e32 v10, 0xbfb8aa3b, v10
	v_exp_f32_e32 v21, v21
	v_mul_f32_e32 v9, 0xbfb8aa3b, v9
	v_exp_f32_e32 v29, v29
	v_lshlrev_b32_e32 v54, 16, v4
	v_and_b32_e32 v55, 0xffff0000, v4
	v_mul_f32_e32 v4, 0xbfb8aa3b, v11
	v_exp_f32_e32 v8, v8
	v_exp_f32_e32 v10, v10
	v_exp_f32_e32 v9, v9
	v_exp_f32_e32 v11, v4
	v_pk_mul_f32 v[54:55], v[54:55], s[74:75] op_sel_hi:[1,0]
	v_lshlrev_b32_e32 v58, 16, v5
	v_pk_mul_f32 v[28:29], v[54:55], v[28:29]
	v_pk_mul_f32 v[20:21], v[54:55], v[20:21]
	v_lshlrev_b32_e32 v54, 16, v0
	v_and_b32_e32 v55, 0xffff0000, v0
	s_waitcnt lgkmcnt(5)
	v_mul_f32_e32 v0, 0x3fb8aa3b, v12
	v_pk_mul_f32 v[10:11], v[10:11], v[54:55]
	v_pk_mul_f32 v[8:9], v[8:9], v[54:55]
	v_exp_f32_e32 v54, v0
	v_mul_f32_e32 v0, 0xbfb8aa3b, v12
	v_exp_f32_e32 v12, v0
	s_waitcnt lgkmcnt(2)
	v_mul_f32_e32 v0, 0x3fb8aa3b, v22
	v_exp_f32_e32 v56, v0
	v_mul_f32_e32 v0, 0xbfb8aa3b, v22
	v_exp_f32_e32 v4, v0
	v_mul_f32_e32 v0, 0x3fb8aa3b, v13
	v_exp_f32_e32 v55, v0
	v_mul_f32_e32 v0, 0xbfb8aa3b, v13
	v_exp_f32_e32 v13, v0
	v_mul_f32_e32 v0, 0x3fb8aa3b, v23
	v_exp_f32_e32 v57, v0
	v_mul_f32_e32 v0, 0xbfb8aa3b, v23
	v_and_b32_e32 v59, 0xffff0000, v5
	v_exp_f32_e32 v5, v0
	v_lshlrev_b32_e32 v0, 16, v1
	v_and_b32_e32 v1, 0xffff0000, v1
	v_pk_mul_f32 v[12:13], v[12:13], v[0:1]
	v_pk_mul_f32 v[4:5], v[4:5], v[0:1]
	v_mul_f32_e32 v1, 0xbfb8aa3b, v14
	v_pk_mul_f32 v[58:59], v[58:59], s[74:75] op_sel_hi:[1,0]
	v_mul_f32_e32 v0, 0x3fb8aa3b, v14
	v_exp_f32_e32 v14, v1
	s_waitcnt lgkmcnt(1)
	v_mul_f32_e32 v1, 0x3fb8aa3b, v24
	v_pk_mul_f32 v[22:23], v[58:59], v[54:55]
	v_exp_f32_e32 v54, v1
	v_mul_f32_e32 v1, 0xbfb8aa3b, v24
	v_exp_f32_e32 v24, v1
	v_mul_f32_e32 v1, 0x3fb8aa3b, v15
	v_mul_f32_e32 v49, 0x3fb8aa3b, v25
	v_pk_mul_f32 v[56:57], v[58:59], v[56:57]
	v_exp_f32_e32 v0, v0
	v_exp_f32_e32 v1, v1
	v_mul_f32_e32 v15, 0xbfb8aa3b, v15
	v_exp_f32_e32 v55, v49
	v_lshlrev_b32_e32 v58, 16, v6
	v_and_b32_e32 v59, 0xffff0000, v6
	v_mul_f32_e32 v6, 0xbfb8aa3b, v25
	v_exp_f32_e32 v15, v15
	v_exp_f32_e32 v25, v6
	v_pk_mul_f32 v[58:59], v[58:59], s[74:75] op_sel_hi:[1,0]
	v_lshlrev_b32_e32 v62, 16, v7
	v_pk_mul_f32 v[54:55], v[58:59], v[54:55]
	v_pk_mul_f32 v[58:59], v[58:59], v[0:1]
	v_lshlrev_b32_e32 v0, 16, v2
	v_and_b32_e32 v1, 0xffff0000, v2
	v_pk_mul_f32 v[24:25], v[24:25], v[0:1]
	v_pk_mul_f32 v[14:15], v[14:15], v[0:1]
	v_mul_f32_e32 v1, 0xbfb8aa3b, v18
	v_mul_f32_e32 v0, 0x3fb8aa3b, v18
	v_exp_f32_e32 v18, v1
	s_waitcnt lgkmcnt(0)
	v_mul_f32_e32 v1, 0x3fb8aa3b, v26
	v_exp_f32_e32 v60, v1
	v_mul_f32_e32 v1, 0xbfb8aa3b, v26
	v_mul_f32_e32 v2, 0xbfb8aa3b, v19
	v_exp_f32_e32 v6, v1
	v_mul_f32_e32 v1, 0x3fb8aa3b, v19
	v_exp_f32_e32 v19, v2
	v_mul_f32_e32 v2, 0x3fb8aa3b, v27
	v_exp_f32_e32 v0, v0
	v_exp_f32_e32 v1, v1
	v_exp_f32_e32 v61, v2
	v_mul_f32_e32 v2, 0xbfb8aa3b, v27
	v_and_b32_e32 v63, 0xffff0000, v7
	v_exp_f32_e32 v7, v2
	v_pk_mul_f32 v[62:63], v[62:63], s[74:75] op_sel_hi:[1,0]
	v_cvt_pk_bf16_f32 v2, v58, v59
	v_pk_mul_f32 v[26:27], v[62:63], v[0:1]
	v_lshlrev_b32_e32 v0, 16, v3
	v_and_b32_e32 v1, 0xffff0000, v3
	v_pk_mul_f32 v[6:7], v[6:7], v[0:1]
	v_pk_mul_f32 v[18:19], v[18:19], v[0:1]
	v_cvt_pk_bf16_f32 v0, v20, v21
	v_cvt_pk_bf16_f32 v1, v22, v23
	v_cvt_pk_bf16_f32 v3, v26, v27
	v_pk_mul_f32 v[60:61], v[62:63], v[60:61]
	ds_write_b128 v92, v[0:3] offset:128
	v_cvt_pk_bf16_f32 v0, v8, v9
	v_cvt_pk_bf16_f32 v1, v12, v13
	v_cvt_pk_bf16_f32 v2, v14, v15
	v_cvt_pk_bf16_f32 v3, v18, v19
	ds_write_b128 v92, v[0:3] offset:17536
	v_cvt_pk_bf16_f32 v0, v28, v29
	v_cvt_pk_bf16_f32 v1, v56, v57
	v_cvt_pk_bf16_f32 v2, v54, v55
	v_cvt_pk_bf16_f32 v3, v60, v61
	ds_write_b128 v92, v[0:3] offset:34944
	v_cvt_pk_bf16_f32 v0, v10, v11
	v_cvt_pk_bf16_f32 v1, v4, v5
	v_cvt_pk_bf16_f32 v2, v24, v25
	v_cvt_pk_bf16_f32 v3, v6, v7
	ds_write_b128 v92, v[0:3] offset:52352
	s_waitcnt lgkmcnt(0)
	s_barrier
	s_waitcnt vmcnt(12)
	v_mov_b32_e32 v0, v166
	v_mov_b32_e32 v1, v167
	v_mov_b32_e32 v2, v168
	v_mov_b32_e32 v3, v169
	v_mov_b32_e32 v4, v170
	v_mov_b32_e32 v5, v171
	v_mov_b32_e32 v6, v172
	v_mov_b32_e32 v7, v173
	v_readlane_b32 s99, v244, 25
	v_lshrrev_b32_e32 v210, 4, v144
	v_and_b32_e32 v211, 15, v144
	v_lshl_add_u32 v210, s99, 4, v210
	v_mul_u32_u24_e32 v210, 0x110, v210
	v_lshl_add_u32 v210, v211, 4, v210
	v_add_u32_e32 v186, 0x16c00, v210
	v_add_u32_e32 v210, 0x7000, v210
	s_waitcnt vmcnt(4)
	ds_write_b128 v210, v[192:195]
	ds_write_b128 v210, v[196:199] offset:1088
	ds_write_b128 v210, v[232:235] offset:2176
	ds_write_b128 v210, v[236:239] offset:3264
	s_lshr_b32 s99, s99, 2
	s_mul_i32 s100, s99, 0x4400
	v_add_u32_e32 v186, s100, v186
	v_lshrrev_b32_e32 v211, 4, v144
	v_and_b32_e32 v210, 15, v144
	v_lshl_add_u32 v210, s99, 6, v210
	v_mul_u32_u24_e32 v210, 0x110, v210
	v_lshl_add_u32 v210, v211, 4, v210
	v_add_u32_e32 v211, 0x16c00, v210
	v_add_u32_e32 v211, s100, v211
	v_add_u32_e32 v210, 0x7000, v210
	ds_write_b16 v103, v0
	ds_write_b16_d16_hi v103, v0 offset:144
	ds_write_b16 v103, v1 offset:288
	ds_write_b16_d16_hi v103, v1 offset:432
	ds_write_b16 v103, v2 offset:576
	ds_write_b16_d16_hi v103, v2 offset:720
	ds_write_b16 v103, v3 offset:864
	ds_write_b16_d16_hi v104, v3
	ds_write_b16 v103, v4 offset:9216
	ds_write_b16_d16_hi v103, v4 offset:9360
	ds_write_b16 v103, v5 offset:9504
	ds_write_b16_d16_hi v103, v5 offset:9648
	ds_write_b16 v103, v6 offset:9792
	ds_write_b16_d16_hi v103, v6 offset:9936
	ds_write_b16 v103, v7 offset:10080
	ds_write_b16_d16_hi v103, v7 offset:10224
	ds_read_b128 v[0:3], v93
	ds_read_b128 v[4:7], v95 offset:17408
	ds_read_b128 v[8:11], v94
	ds_read_b128 v[12:15], v93 offset:64
	ds_read_b128 v[16:19], v95 offset:17472
	s_waitcnt lgkmcnt(3)
	v_mfma_f32_16x16x32_bf16 v[0:3], v[0:3], v[4:7], 0
	ds_read_b128 v[4:7], v95 offset:52224
	ds_read_b128 v[20:23], v94 offset:64
	ds_read_b128 v[24:27], v95 offset:52288
	s_waitcnt lgkmcnt(2)
	v_mfma_f32_16x16x32_bf16 v[4:7], v[8:11], v[4:7], 0
	v_mfma_f32_16x16x32_bf16 v[0:3], v[12:15], v[16:19], v[0:3]
	ds_read_b128 v[8:11], v93 offset:128
	ds_read_b128 v[12:15], v95 offset:17536
	s_waitcnt lgkmcnt(2)
	v_mfma_f32_16x16x32_bf16 v[4:7], v[20:23], v[24:27], v[4:7]
	ds_read_b128 v[16:19], v94 offset:128
	ds_read_b128 v[20:23], v93 offset:192
	ds_read_b128 v[24:27], v95 offset:17600
	s_waitcnt lgkmcnt(3)
	v_mfma_f32_16x16x32_bf16 v[0:3], v[8:11], v[12:15], v[0:3]
	ds_read_b128 v[8:11], v95 offset:52352
	ds_read_b128 v[12:15], v94 offset:192
	ds_read_b128 v[54:57], v95 offset:52416
	s_waitcnt lgkmcnt(2)
	v_mfma_f32_16x16x32_bf16 v[4:7], v[16:19], v[8:11], v[4:7]
	v_mfma_f32_16x16x32_bf16 v[0:3], v[20:23], v[24:27], v[0:3]
	s_waitcnt lgkmcnt(0)
	v_mfma_f32_16x16x32_bf16 v[4:7], v[12:15], v[54:57], v[4:7]
	s_nop 5
	v_cndmask_b32_e64 v0, v0, 0, s[12:13]
	s_nop 0
	v_cndmask_b32_e64 v4, v4, 0, s[14:15]
	v_add_f32_e32 v0, v0, v4
	v_cvt_pk_bf16_f32 v0, v0, s0
	ds_write_b16 v105, v0 offset:18432
	v_cndmask_b32_e64 v0, v1, 0, s[16:17]
	v_cndmask_b32_e64 v1, 0, v5, s[12:13]
	v_add_f32_e32 v0, v0, v1
	v_cvt_pk_bf16_f32 v0, v0, s0
	ds_write_b16 v105, v0 offset:18576
	v_cndmask_b32_e64 v0, v2, 0, s[18:19]
	v_cndmask_b32_e64 v1, v6, 0, s[20:21]
	v_add_f32_e32 v0, v0, v1
	v_cvt_pk_bf16_f32 v0, v0, s0
	ds_write_b16 v105, v0 offset:18720
	v_cndmask_b32_e64 v0, v3, 0, s[22:23]
	v_cndmask_b32_e64 v1, v7, 0, s[24:25]
	v_add_f32_e32 v0, v0, v1
	v_cvt_pk_bf16_f32 v0, v0, s0
	ds_write_b16 v105, v0 offset:18864
	ds_read_b128 v[0:3], v93
	ds_read_b128 v[4:7], v96 offset:17408
	ds_read_b128 v[8:11], v94
	ds_read_b128 v[12:15], v93 offset:64
	ds_read_b128 v[16:19], v96 offset:17472
	s_waitcnt lgkmcnt(3)
	v_mfma_f32_16x16x32_bf16 v[0:3], v[0:3], v[4:7], 0
	ds_read_b128 v[4:7], v96 offset:52224
	ds_read_b128 v[20:23], v94 offset:64
	ds_read_b128 v[24:27], v96 offset:52288
	s_waitcnt lgkmcnt(2)
	v_mfma_f32_16x16x32_bf16 v[4:7], v[8:11], v[4:7], 0
	v_mfma_f32_16x16x32_bf16 v[0:3], v[12:15], v[16:19], v[0:3]
	ds_read_b128 v[8:11], v93 offset:128
	ds_read_b128 v[12:15], v96 offset:17536
	s_waitcnt lgkmcnt(2)
	v_mfma_f32_16x16x32_bf16 v[4:7], v[20:23], v[24:27], v[4:7]
	ds_read_b128 v[16:19], v94 offset:128
	ds_read_b128 v[20:23], v93 offset:192
	ds_read_b128 v[24:27], v96 offset:17600
	s_waitcnt lgkmcnt(3)
	v_mfma_f32_16x16x32_bf16 v[0:3], v[8:11], v[12:15], v[0:3]
	ds_read_b128 v[8:11], v96 offset:52352
	ds_read_b128 v[12:15], v94 offset:192
	ds_read_b128 v[54:57], v96 offset:52416
	s_waitcnt lgkmcnt(2)
	v_mfma_f32_16x16x32_bf16 v[4:7], v[16:19], v[8:11], v[4:7]
	v_mfma_f32_16x16x32_bf16 v[0:3], v[20:23], v[24:27], v[0:3]
	s_waitcnt lgkmcnt(0)
	v_mfma_f32_16x16x32_bf16 v[4:7], v[12:15], v[54:57], v[4:7]
	s_nop 5
	v_cndmask_b32_e64 v0, v0, 0, s[26:27]
	s_nop 0
	v_cndmask_b32_e64 v4, v4, 0, s[28:29]
	v_add_f32_e32 v0, v0, v4
	v_cvt_pk_bf16_f32 v0, v0, s0
	ds_write_b16 v105, v0 offset:18464
	v_cndmask_b32_e64 v0, v1, 0, s[30:31]
	v_cndmask_b32_e64 v1, 0, v5, s[26:27]
	v_add_f32_e32 v0, v0, v1
	v_cvt_pk_bf16_f32 v0, v0, s0
	ds_write_b16 v105, v0 offset:18608
	v_cndmask_b32_e64 v0, v2, 0, s[34:35]
	v_cndmask_b32_e64 v1, v6, 0, s[36:37]
	v_add_f32_e32 v0, v0, v1
	v_cvt_pk_bf16_f32 v0, v0, s0
	ds_write_b16 v105, v0 offset:18752
	v_cndmask_b32_e64 v0, v3, 0, s[38:39]
	v_cndmask_b32_e64 v1, v7, 0, s[40:41]
	v_add_f32_e32 v0, v0, v1
	v_cvt_pk_bf16_f32 v0, v0, s0
	s_lshl_b32 s0, s85, 3
	s_or_b32 s0, s1, s0
	s_ashr_i32 s1, s0, 31
	s_lshl_b64 s[46:47], s[0:1], 21
	s_or_b32 s0, s0, 1
	s_ashr_i32 s1, s0, 31
	s_lshl_b64 s[0:1], s[0:1], 21
	s_add_u32 s48, s52, s0
	s_addc_u32 s49, s53, s1
	s_add_u32 s0, s52, s46
	s_addc_u32 s1, s53, s47
	s_add_u32 s0, s0, s45
	s_addc_u32 s1, s1, 0
	v_lshl_add_u64 v[28:29], s[0:1], 0, v[30:31]
	v_lshl_add_u64 v[24:25], v[28:29], 0, v[36:37]
	ds_write_b16 v105, v0 offset:18896
	s_waitcnt lgkmcnt(0)
	s_barrier
	s_waitcnt vmcnt(0)
	ds_write_b128 v186, v[150:153]
	ds_write_b128 v186, v[154:157] offset:1088
	ds_write_b128 v186, v[158:161] offset:2176
	ds_write_b128 v186, v[162:165] offset:3264
	ds_read_b128 v[16:19], v106 offset:18432
	ds_read_b128 v[20:23], v106 offset:18496
	ds_read_b128 v[58:61], v107
	ds_read_b128 v[74:77], v107 offset:64
	ds_read_b128 v[54:57], v98
	ds_read_b128 v[62:65], v98 offset:64
	ds_read_b128 v[66:69], v98 offset:128
	ds_read_b128 v[70:73], v98 offset:192
	ds_read_b128 v[194:197], v210
	ds_read_b128 v[198:201], v210 offset:64
	ds_read_b128 v[202:205], v210 offset:128
	ds_read_b128 v[206:209], v210 offset:192
	s_waitcnt lgkmcnt(9)
	v_mfma_f32_16x16x32_bf16 v[12:15], v[58:61], v[16:19], 0
	s_waitcnt lgkmcnt(8)
	v_mfma_f32_16x16x32_bf16 v[12:15], v[74:77], v[20:23], v[12:15]
	ds_read_b128 v[58:61], v107 offset:2304
	ds_read_b128 v[74:77], v107 offset:2368
	ds_read_b128 v[228:231], v210 offset:4352
	ds_read_b128 v[232:235], v210 offset:4416
	ds_read_b128 v[236:239], v210 offset:4480
	ds_read_b128 v[240:243], v210 offset:4544
	s_waitcnt lgkmcnt(13)
	s_waitcnt lgkmcnt(9)
	v_mfma_f32_16x16x32_bf16 v[12:15], v[194:197], v[54:57], v[12:15]
	s_waitcnt lgkmcnt(12)
	s_waitcnt lgkmcnt(8)
	v_mfma_f32_16x16x32_bf16 v[12:15], v[198:201], v[62:65], v[12:15]
	s_waitcnt lgkmcnt(11)
	s_waitcnt lgkmcnt(7)
	v_mfma_f32_16x16x32_bf16 v[12:15], v[202:205], v[66:69], v[12:15]
	s_waitcnt lgkmcnt(10)
	s_waitcnt lgkmcnt(6)
	v_mfma_f32_16x16x32_bf16 v[12:15], v[206:209], v[70:73], v[12:15]
	s_waitcnt lgkmcnt(5)
	v_mfma_f32_16x16x32_bf16 v[8:11], v[58:61], v[16:19], 0
	s_waitcnt lgkmcnt(4)
	v_mfma_f32_16x16x32_bf16 v[8:11], v[74:77], v[20:23], v[8:11]
	ds_read_b128 v[58:61], v107 offset:4608
	ds_read_b128 v[74:77], v107 offset:4672
	ds_read_b128 v[194:197], v210 offset:8704
	ds_read_b128 v[198:201], v210 offset:8768
	ds_read_b128 v[202:205], v210 offset:8832
	ds_read_b128 v[206:209], v210 offset:8896
	s_waitcnt lgkmcnt(9)
	v_mfma_f32_16x16x32_bf16 v[8:11], v[228:231], v[54:57], v[8:11]
	s_waitcnt lgkmcnt(8)
	v_mfma_f32_16x16x32_bf16 v[8:11], v[232:235], v[62:65], v[8:11]
	s_waitcnt lgkmcnt(7)
	v_mfma_f32_16x16x32_bf16 v[8:11], v[236:239], v[66:69], v[8:11]
	s_waitcnt lgkmcnt(6)
	v_mfma_f32_16x16x32_bf16 v[8:11], v[240:243], v[70:73], v[8:11]
	s_waitcnt lgkmcnt(5)
	v_mfma_f32_16x16x32_bf16 v[4:7], v[58:61], v[16:19], 0
	s_waitcnt lgkmcnt(4)
	v_mfma_f32_16x16x32_bf16 v[4:7], v[74:77], v[20:23], v[4:7]
	ds_read_b128 v[58:61], v108
	ds_read_b128 v[74:77], v108 offset:64
	ds_read_b128 v[228:231], v210 offset:13056
	ds_read_b128 v[232:235], v210 offset:13120
	ds_read_b128 v[236:239], v210 offset:13184
	ds_read_b128 v[240:243], v210 offset:13248
	s_waitcnt lgkmcnt(9)
	v_mfma_f32_16x16x32_bf16 v[4:7], v[194:197], v[54:57], v[4:7]
	s_waitcnt lgkmcnt(8)
	v_mfma_f32_16x16x32_bf16 v[4:7], v[198:201], v[62:65], v[4:7]
	s_waitcnt lgkmcnt(7)
	v_mfma_f32_16x16x32_bf16 v[4:7], v[202:205], v[66:69], v[4:7]
	s_waitcnt lgkmcnt(6)
	v_mfma_f32_16x16x32_bf16 v[4:7], v[206:209], v[70:73], v[4:7]
	s_waitcnt lgkmcnt(5)
	v_mfma_f32_16x16x32_bf16 v[0:3], v[58:61], v[16:19], 0
	s_waitcnt lgkmcnt(4)
	v_mfma_f32_16x16x32_bf16 v[0:3], v[74:77], v[20:23], v[0:3]
	ds_read_b128 v[24:27], v98 offset:34816
	ds_read_b128 v[78:81], v98 offset:34880
	ds_read_b128 v[114:117], v98 offset:34944
	ds_read_b128 v[118:121], v98 offset:35008
	s_waitcnt lgkmcnt(7)
	v_mfma_f32_16x16x32_bf16 v[0:3], v[228:231], v[54:57], v[0:3]
	s_waitcnt lgkmcnt(6)
	v_mfma_f32_16x16x32_bf16 v[0:3], v[232:235], v[62:65], v[0:3]
	s_waitcnt lgkmcnt(5)
	v_mfma_f32_16x16x32_bf16 v[0:3], v[236:239], v[66:69], v[0:3]
	s_waitcnt lgkmcnt(4)
	v_mfma_f32_16x16x32_bf16 v[0:3], v[240:243], v[70:73], v[0:3]
	s_waitcnt lgkmcnt(0)
	s_barrier
	ds_read_b128 v[194:197], v211
	ds_read_b128 v[198:201], v211 offset:64
	ds_read_b128 v[202:205], v211 offset:128
	ds_read_b128 v[206:209], v211 offset:192
	ds_read_b128 v[228:231], v211 offset:4352
	ds_read_b128 v[232:235], v211 offset:4416
	ds_read_b128 v[236:239], v211 offset:4480
	ds_read_b128 v[240:243], v211 offset:4544
	s_waitcnt lgkmcnt(7)
	v_mfma_f32_16x16x32_bf16 v[12:15], v[194:197], v[24:27], v[12:15]
	s_waitcnt lgkmcnt(6)
	v_mfma_f32_16x16x32_bf16 v[12:15], v[198:201], v[78:81], v[12:15]
	s_waitcnt lgkmcnt(5)
	v_mfma_f32_16x16x32_bf16 v[12:15], v[202:205], v[114:117], v[12:15]
	s_waitcnt lgkmcnt(4)
	v_mfma_f32_16x16x32_bf16 v[12:15], v[206:209], v[118:121], v[12:15]
	ds_read_b128 v[194:197], v211 offset:8704
	ds_read_b128 v[198:201], v211 offset:8768
	ds_read_b128 v[202:205], v211 offset:8832
	ds_read_b128 v[206:209], v211 offset:8896
	s_waitcnt lgkmcnt(7)
	v_mfma_f32_16x16x32_bf16 v[8:11], v[228:231], v[24:27], v[8:11]
	s_waitcnt lgkmcnt(6)
	v_mfma_f32_16x16x32_bf16 v[8:11], v[232:235], v[78:81], v[8:11]
	s_waitcnt lgkmcnt(5)
	v_mfma_f32_16x16x32_bf16 v[8:11], v[236:239], v[114:117], v[8:11]
	s_waitcnt lgkmcnt(4)
	v_mfma_f32_16x16x32_bf16 v[8:11], v[240:243], v[118:121], v[8:11]
	v_mul_f32_e32 v130, v13, v13
	v_mul_f32_e32 v131, v15, v15
	v_fmac_f32_e32 v130, v12, v12
	v_fmac_f32_e32 v131, v14, v14
	v_add_f32_e32 v130, v130, v131
	v_mov_b32_e32 v132, v130
	ds_read_b128 v[228:231], v211 offset:13056
	ds_read_b128 v[232:235], v211 offset:13120
	ds_read_b128 v[236:239], v211 offset:13184
	ds_read_b128 v[240:243], v211 offset:13248
	s_waitcnt lgkmcnt(7)
	v_mfma_f32_16x16x32_bf16 v[4:7], v[194:197], v[24:27], v[4:7]
	s_waitcnt lgkmcnt(6)
	v_mfma_f32_16x16x32_bf16 v[4:7], v[198:201], v[78:81], v[4:7]
	s_waitcnt lgkmcnt(5)
	v_mfma_f32_16x16x32_bf16 v[4:7], v[202:205], v[114:117], v[4:7]
	s_waitcnt lgkmcnt(4)
	v_mfma_f32_16x16x32_bf16 v[4:7], v[206:209], v[118:121], v[4:7]
	v_mul_f32_e32 v130, v9, v9
	v_mul_f32_e32 v131, v11, v11
	v_fmac_f32_e32 v130, v8, v8
	v_fmac_f32_e32 v131, v10, v10
	v_add_f32_e32 v130, v130, v131
	v_add_f32_e32 v132, v132, v130
	s_waitcnt lgkmcnt(3)
	v_mfma_f32_16x16x32_bf16 v[0:3], v[228:231], v[24:27], v[0:3]
	s_waitcnt lgkmcnt(2)
	v_mfma_f32_16x16x32_bf16 v[0:3], v[232:235], v[78:81], v[0:3]
	s_waitcnt lgkmcnt(1)
	v_mfma_f32_16x16x32_bf16 v[0:3], v[236:239], v[114:117], v[0:3]
	s_waitcnt lgkmcnt(0)
	v_mfma_f32_16x16x32_bf16 v[0:3], v[240:243], v[118:121], v[0:3]
	v_mul_f32_e32 v130, v5, v5
	v_mul_f32_e32 v131, v7, v7
	v_fmac_f32_e32 v130, v4, v4
	v_fmac_f32_e32 v131, v6, v6
	v_add_f32_e32 v130, v130, v131
	v_add_f32_e32 v132, v132, v130
	s_nop 7
	s_nop 1
	v_mul_f32_e32 v17, v1, v1
	v_mul_f32_e32 v18, v3, v3
	v_fmac_f32_e32 v17, v0, v0
	v_fmac_f32_e32 v18, v2, v2
	v_add_f32_e32 v17, v17, v18
	v_add_f32_e32 v16, v132, v17
	v_mov_b32_e32 v17, v16
	s_nop 1
	v_permlane16_swap_b32_e32 v17, v16
	s_waitcnt lgkmcnt(0)
	v_add_f32_e32 v16, v16, v17
	v_mov_b32_e32 v17, v16
	s_nop 1
	v_permlane32_swap_b32_e32 v17, v16
	s_and_saveexec_b64 s[0:1], s[42:43]
	s_cbranch_execz .LBB0_819
	s_waitcnt lgkmcnt(0)
	v_add_f32_e32 v16, v16, v17
	ds_write_b32 v99, v16 offset:27648
	s_branch .LBB0_819
